# stack5 + attention row-max chains: redundant canonicalizing v_max x,x,x removed (3->1 after the permlane swap, 3->1 at the diff chain start); bit-identical for non-NaN scores
# baseline (speedup 1.0000x reference)
.LBB0_251:
	v_add_u32_e32 v0, s18, v225
	ds_read_b64_tr_b16 v[192:193], v0 offset:24576
	ds_read_b64_tr_b16 v[194:195], v0 offset:25088
	v_add_f32_e32 v2, v80, v81
	v_add_f32_e32 v2, v82, v2
	v_add_f32_e32 v2, v83, v2
	v_add_f32_e32 v2, v84, v2
	v_add_f32_e32 v2, v85, v2
	v_cvt_pk_bf16_f32 v156, v80, v81
	v_cvt_pk_bf16_f32 v157, v82, v83
	s_waitcnt lgkmcnt(9)
	v_mfma_f32_32x32x16_bf16 v[96:111], v[188:191], v[140:143], v[48:63]
	ds_read_b64_tr_b16 v[188:189], v0 offset:28672
	ds_read_b64_tr_b16 v[190:191], v0 offset:29184
	v_add_f32_e32 v2, v86, v2
	v_add_f32_e32 v2, v87, v2
	v_add_f32_e32 v2, v88, v2
	v_add_f32_e32 v2, v89, v2
	v_cvt_pk_bf16_f32 v158, v84, v85
	v_cvt_pk_bf16_f32 v159, v86, v87
	s_waitcnt lgkmcnt(10)
	v_mfma_f32_32x32x16_bf16 v[112:127], v[184:187], v[140:143], v[48:63]
	ds_read_b64_tr_b16 v[10:11], v0 offset:25600
	ds_read_b64_tr_b16 v[12:13], v0 offset:26112
	v_add_f32_e32 v2, v90, v2
	v_add_f32_e32 v2, v91, v2
	v_add_f32_e32 v2, v92, v2
	v_add_f32_e32 v2, v93, v2
	v_cvt_pk_bf16_f32 v152, v88, v89
	v_cvt_pk_bf16_f32 v153, v90, v91
	s_waitcnt lgkmcnt(11)
	v_mfma_f32_32x32x16_bf16 v[96:111], v[180:183], v[136:139], v[96:111]
	ds_read_b64_tr_b16 v[180:181], v0 offset:29696
	ds_read_b64_tr_b16 v[182:183], v0 offset:30208
	v_add_f32_e32 v2, v94, v2
	v_add_f32_e32 v2, v95, v2
	v_add_f32_e32 v2, v64, v2
	v_add_f32_e32 v2, v65, v2
	v_cvt_pk_bf16_f32 v154, v92, v93
	v_cvt_pk_bf16_f32 v155, v94, v95
	s_waitcnt lgkmcnt(12)
	v_mfma_f32_32x32x16_bf16 v[112:127], v[176:179], v[136:139], v[112:127]
	ds_read_b64_tr_b16 v[176:177], v0 offset:26624
	ds_read_b64_tr_b16 v[178:179], v0 offset:27136
	v_add_f32_e32 v2, v66, v2
	v_add_f32_e32 v2, v67, v2
	v_add_f32_e32 v2, v68, v2
	v_add_f32_e32 v6, v69, v2
	v_cvt_pk_bf16_f32 v148, v64, v65
	v_cvt_pk_bf16_f32 v149, v66, v67
	s_waitcnt lgkmcnt(13)
	v_mfma_f32_32x32x16_bf16 v[96:111], v[172:175], v[132:135], v[96:111]
	ds_read_b64_tr_b16 v[2:3], v0 offset:30720
	ds_read_b64_tr_b16 v[4:5], v0 offset:31232
	v_add_f32_e32 v6, v70, v6
	v_add_f32_e32 v6, v71, v6
	v_add_f32_e32 v6, v72, v6
	v_add_f32_e32 v14, v73, v6
	v_cvt_pk_bf16_f32 v150, v68, v69
	v_cvt_pk_bf16_f32 v151, v70, v71
	s_waitcnt lgkmcnt(14)
	v_mfma_f32_32x32x16_bf16 v[112:127], v[168:171], v[132:135], v[112:127]
	ds_read_b64_tr_b16 v[6:7], v0 offset:27648
	ds_read_b64_tr_b16 v[8:9], v0 offset:28160
	v_add_f32_e32 v14, v74, v14
	v_add_f32_e32 v14, v75, v14
	v_add_f32_e32 v14, v76, v14
	v_add_f32_e32 v14, v77, v14
	v_cvt_pk_bf16_f32 v144, v72, v73
	v_cvt_pk_bf16_f32 v145, v74, v75
	s_waitcnt lgkmcnt(14)
	v_mfma_f32_32x32x16_bf16 v[96:111], v[164:167], v[128:131], v[96:111]
	ds_read_b64_tr_b16 v[164:165], v0 offset:31744
	ds_read_b64_tr_b16 v[166:167], v0 offset:32256
	v_add_f32_e32 v0, v78, v14
	v_add_f32_e32 v0, v79, v0
	v_add_f32_e32 v0, 0, v0
	v_cvt_pk_bf16_f32 v146, v76, v77
	v_cvt_pk_bf16_f32 v147, v78, v79
	v_mfma_f32_32x32x16_bf16 v[112:127], v[160:163], v[128:131], v[112:127]
	v_lshl_add_u64 v[14:15], v[202:203], 0, s[54:55]
	s_add_i32 s18, s69, s38
	s_mov_b32 s19, m0
	s_mov_b32 m0, s18
	s_nop 0
	global_load_lds_dwordx4 v[14:15], off
	s_mov_b32 m0, s19
	v_lshl_add_u64 v[14:15], v[200:201], 0, s[54:55]
	s_add_i32 s18, s7, s59
	s_mov_b32 s19, m0
	s_mov_b32 m0, s18
	s_nop 0
	global_load_lds_dwordx4 v[14:15], off
	s_mov_b32 m0, s19
	ds_read_b128 v[64:67], v204
	ds_read_b128 v[68:71], v204 offset:32
	ds_read_b128 v[72:75], v204 offset:128
	v_add_f32_e32 v0, v230, v0
	s_waitcnt lgkmcnt(2)
	v_pk_add_f32 v[82:83], v[98:99], v[66:67]
	s_waitcnt lgkmcnt(1)
	v_pk_add_f32 v[84:85], v[100:101], v[68:69]
	s_waitcnt lgkmcnt(0)
	v_pk_add_f32 v[14:15], v[112:113], v[72:73]
	v_pk_add_f32 v[66:67], v[114:115], v[74:75]
	ds_read_b128 v[72:75], v204 offset:160
	v_pk_add_f32 v[86:87], v[102:103], v[70:71]
	v_pk_add_f32 v[64:65], v[96:97], v[64:65]
	v_max3_f32 v81, v82, v83, v15
	v_max_f32_e32 v80, v64, v65
	s_waitcnt lgkmcnt(0)
	v_pk_add_f32 v[68:69], v[116:117], v[72:73]
	v_pk_add_f32 v[70:71], v[118:119], v[74:75]
	ds_read_b128 v[72:75], v204 offset:64
	ds_read_b128 v[76:79], v204 offset:192
	v_max3_f32 v80, v80, v14, v66
	v_max3_f32 v80, v80, v67, v84
	v_max3_f32 v81, v81, v86, v87
	s_waitcnt lgkmcnt(1)
	v_pk_add_f32 v[88:89], v[104:105], v[72:73]
	s_waitcnt lgkmcnt(0)
	v_pk_add_f32 v[72:73], v[120:121], v[76:77]
	v_pk_add_f32 v[90:91], v[106:107], v[74:75]
	v_pk_add_f32 v[74:75], v[122:123], v[78:79]
	ds_read_b128 v[76:79], v204 offset:96
	ds_read_b128 v[94:97], v204 offset:224
	v_max3_f32 v80, v80, v85, v68
	v_max3_f32 v81, v81, v70, v71
	v_max3_f32 v80, v80, v69, v88
	v_max3_f32 v81, v81, v90, v91
	s_waitcnt lgkmcnt(1)
	v_pk_add_f32 v[92:93], v[108:109], v[76:77]
	s_waitcnt lgkmcnt(0)
	v_pk_add_f32 v[76:77], v[124:125], v[94:95]
	v_pk_add_f32 v[94:95], v[110:111], v[78:79]
	v_max3_f32 v80, v80, v89, v72
	v_max3_f32 v81, v81, v74, v75
	v_pk_add_f32 v[78:79], v[126:127], v[96:97]
	v_max3_f32 v80, v80, v73, v92
	v_max3_f32 v81, v81, v94, v95
	v_max3_f32 v80, v80, v93, v76
	v_max3_f32 v81, v81, v78, v79
	v_max3_f32 v80, v80, v77, v81
	v_mov_b32_e32 v81, v80
	s_nop 1
	v_permlane32_swap_b32_e32 v80, v81
	v_max_f32_e32 v80, v80, v81
	v_cmp_lt_f32_e32 vcc, s96, v80
	s_cmp_lg_u64 vcc, 0
	s_cselect_b64 s[18:19], -1, 0
	s_cbranch_vccnz .LBB0_259

.LBB0_254:
	s_add_i32 s18, s7, 0x2000
	s_cmpk_lg_i32 s7, 0x4000
	s_cselect_b32 s60, s18, 0
	v_add_u32_e32 v14, s69, v225
	ds_read_b64_tr_b16 v[168:169], v14 offset:24576
	ds_read_b64_tr_b16 v[170:171], v14 offset:25088
	v_add_f32_e32 v2, v80, v81
	v_add_f32_e32 v2, v82, v2
	v_add_f32_e32 v2, v83, v2
	v_add_f32_e32 v2, v84, v2
	v_add_f32_e32 v2, v85, v2
	v_cvt_pk_bf16_f32 v156, v80, v81
	v_cvt_pk_bf16_f32 v157, v82, v83
	s_waitcnt lgkmcnt(9)
	v_mfma_f32_32x32x16_bf16 v[96:111], v[112:115], v[140:143], v[48:63]
	ds_read_b64_tr_b16 v[164:165], v14 offset:28672
	ds_read_b64_tr_b16 v[166:167], v14 offset:29184
	v_add_f32_e32 v2, v86, v2
	v_add_f32_e32 v2, v87, v2
	v_add_f32_e32 v2, v88, v2
	v_add_f32_e32 v2, v89, v2
	v_cvt_pk_bf16_f32 v158, v84, v85
	v_cvt_pk_bf16_f32 v159, v86, v87
	s_waitcnt lgkmcnt(10)
	v_mfma_f32_32x32x16_bf16 v[112:127], v[160:163], v[140:143], v[48:63]
	ds_read_b64_tr_b16 v[10:11], v14 offset:25600
	ds_read_b64_tr_b16 v[12:13], v14 offset:26112
	v_add_f32_e32 v2, v90, v2
	v_add_f32_e32 v2, v91, v2
	v_add_f32_e32 v2, v92, v2
	v_add_f32_e32 v2, v93, v2
	v_cvt_pk_bf16_f32 v152, v88, v89
	v_cvt_pk_bf16_f32 v153, v90, v91
	s_waitcnt lgkmcnt(11)
	v_mfma_f32_32x32x16_bf16 v[96:111], v[192:195], v[136:139], v[96:111]
	ds_read_b64_tr_b16 v[160:161], v14 offset:29696
	ds_read_b64_tr_b16 v[162:163], v14 offset:30208
	v_add_f32_e32 v2, v94, v2
	v_add_f32_e32 v2, v95, v2
	v_add_f32_e32 v2, v64, v2
	v_add_f32_e32 v2, v65, v2
	v_cvt_pk_bf16_f32 v154, v92, v93
	v_cvt_pk_bf16_f32 v155, v94, v95
	s_waitcnt lgkmcnt(12)
	v_mfma_f32_32x32x16_bf16 v[112:127], v[188:191], v[136:139], v[112:127]
	ds_read_b64_tr_b16 v[196:197], v14 offset:26624
	ds_read_b64_tr_b16 v[198:199], v14 offset:27136
	v_add_f32_e32 v2, v66, v2
	v_add_f32_e32 v2, v67, v2
	v_add_f32_e32 v2, v68, v2
	v_add_f32_e32 v6, v69, v2
	v_cvt_pk_bf16_f32 v148, v64, v65
	v_cvt_pk_bf16_f32 v149, v66, v67
	s_waitcnt lgkmcnt(13)
	v_mfma_f32_32x32x16_bf16 v[96:111], v[184:187], v[132:135], v[96:111]
	ds_read_b64_tr_b16 v[2:3], v14 offset:30720
	ds_read_b64_tr_b16 v[4:5], v14 offset:31232
	v_add_f32_e32 v6, v70, v6
	v_add_f32_e32 v6, v71, v6
	v_add_f32_e32 v6, v72, v6
	v_add_f32_e32 v15, v73, v6
	v_cvt_pk_bf16_f32 v150, v68, v69
	v_cvt_pk_bf16_f32 v151, v70, v71
	s_waitcnt lgkmcnt(14)
	v_mfma_f32_32x32x16_bf16 v[112:127], v[180:183], v[132:135], v[112:127]
	ds_read_b64_tr_b16 v[6:7], v14 offset:27648
	ds_read_b64_tr_b16 v[8:9], v14 offset:28160
	v_add_f32_e32 v15, v74, v15
	v_add_f32_e32 v15, v75, v15
	v_add_f32_e32 v15, v76, v15
	v_add_f32_e32 v15, v77, v15
	v_cvt_pk_bf16_f32 v144, v72, v73
	v_cvt_pk_bf16_f32 v145, v74, v75
	s_waitcnt lgkmcnt(14)
	v_mfma_f32_32x32x16_bf16 v[96:111], v[176:179], v[128:131], v[96:111]
	ds_read_b64_tr_b16 v[192:193], v14 offset:31744
	ds_read_b64_tr_b16 v[194:195], v14 offset:32256
	v_add_f32_e32 v14, v78, v15
	v_add_f32_e32 v14, v79, v14
	v_add_f32_e32 v80, 0, v14
	v_cvt_pk_bf16_f32 v146, v76, v77
	v_cvt_pk_bf16_f32 v147, v78, v79
	v_mfma_f32_32x32x16_bf16 v[112:127], v[172:175], v[128:131], v[112:127]
	s_add_i32 s18, s7, s38
	s_mov_b32 s19, m0
	s_mov_b32 m0, s18
	s_nop 0
	global_load_lds_dwordx4 v[202:203], off
	s_mov_b32 m0, s19
	s_add_i32 s18, s60, s59
	s_mov_b32 s19, m0
	s_mov_b32 m0, s18
	s_nop 0
	global_load_lds_dwordx4 v[200:201], off
	s_mov_b32 m0, s19
	ds_read_b128 v[64:67], v204 offset:256
	ds_read_b128 v[68:71], v204 offset:288
	ds_read_b128 v[72:75], v204 offset:384
	v_add_f32_e32 v230, v0, v80
	s_waitcnt lgkmcnt(2)
	v_pk_add_f32 v[82:83], v[98:99], v[66:67]
	s_waitcnt lgkmcnt(1)
	v_pk_add_f32 v[84:85], v[100:101], v[68:69]
	s_waitcnt lgkmcnt(0)
	s_nop 0
	v_pk_add_f32 v[14:15], v[112:113], v[72:73]
	v_pk_add_f32 v[66:67], v[114:115], v[74:75]
	ds_read_b128 v[72:75], v204 offset:416
	v_pk_add_f32 v[86:87], v[102:103], v[70:71]
	v_pk_add_f32 v[64:65], v[96:97], v[64:65]
	s_waitcnt lgkmcnt(0)
	v_pk_add_f32 v[68:69], v[116:117], v[72:73]
	v_pk_add_f32 v[70:71], v[118:119], v[74:75]
	ds_read_b128 v[72:75], v204 offset:320
	ds_read_b128 v[76:79], v204 offset:448
	v_max_f32_e32 v81, v64, v65
	v_max3_f32 v81, v81, v14, v66
	v_max3_f32 v81, v81, v67, v84
	s_waitcnt lgkmcnt(1)
	v_pk_add_f32 v[88:89], v[104:105], v[72:73]
	s_waitcnt lgkmcnt(0)
	v_pk_add_f32 v[72:73], v[120:121], v[76:77]
	v_pk_add_f32 v[90:91], v[106:107], v[74:75]
	v_pk_add_f32 v[74:75], v[122:123], v[78:79]
	ds_read_b128 v[76:79], v204 offset:352
	ds_read_b128 v[94:97], v204 offset:480
	v_max3_f32 v81, v81, v85, v68
	v_max3_f32 v81, v81, v69, v88
	v_max3_f32 v81, v81, v89, v72
	s_waitcnt lgkmcnt(1)
	v_pk_add_f32 v[92:93], v[108:109], v[76:77]
	s_waitcnt lgkmcnt(0)
	v_pk_add_f32 v[76:77], v[124:125], v[94:95]
	v_pk_add_f32 v[94:95], v[110:111], v[78:79]
	v_pk_add_f32 v[78:79], v[126:127], v[96:97]
	v_max3_f32 v96, v82, v83, v15
	v_max3_f32 v96, v96, v86, v87
	v_max3_f32 v96, v96, v70, v71
	v_max3_f32 v96, v96, v90, v91
	v_max3_f32 v96, v96, v74, v75
	v_max3_f32 v81, v81, v73, v92
	v_max3_f32 v96, v96, v94, v95
	v_max3_f32 v81, v81, v93, v76
	v_max3_f32 v96, v96, v78, v79
	v_max3_f32 v0, v81, v77, v96
	v_mov_b32_e32 v80, v0
	s_nop 1
	v_permlane32_swap_b32_e32 v0, v80
	v_max_f32_e32 v0, v0, v80
	v_cmp_lt_f32_e32 vcc, s96, v0
	s_cmp_lg_u64 vcc, 0
	s_cselect_b64 s[18:19], -1, 0
	s_cbranch_vccnz .LBB0_262

; __device__ __forceinline__ void cmask(f32x16&p0,f32x16&p1,int jb,int qrel,int hi){
;   const float NEG=-INFINITY; int kb=64*jb+4*hi;
;   #pragma unroll
;   for(int r=0;r<16;++r){int kv=kb+(r&3)+8*(r>>2); if(kv>qrel)p0[r]=NEG; if(kv+32>qrel)p1[r]=NEG;}
; }
.LBB0_267:
	v_add_u32_e32 v0, s72, v225
	ds_read_b64_tr_b16 v[6:7], v0 offset:24576
	ds_read_b64_tr_b16 v[8:9], v0 offset:25088
	v_add_f32_e32 v2, v80, v81
	v_add_f32_e32 v2, v82, v2
	v_add_f32_e32 v2, v83, v2
	v_add_f32_e32 v2, v84, v2
	v_add_f32_e32 v10, v85, v2
	v_cvt_pk_bf16_f32 v156, v80, v81
	v_cvt_pk_bf16_f32 v157, v82, v83
	s_waitcnt lgkmcnt(3)
	v_mfma_f32_32x32x16_bf16 v[96:111], v[188:191], v[140:143], v[48:63]
	ds_read_b64_tr_b16 v[2:3], v0 offset:28672
	ds_read_b64_tr_b16 v[4:5], v0 offset:29184
	s_waitcnt lgkmcnt(4)
	v_mfma_f32_32x32x16_bf16 v[48:63], v[184:187], v[140:143], v[48:63]
	v_add_f32_e32 v10, v86, v10
	v_add_f32_e32 v10, v87, v10
	v_add_f32_e32 v10, v88, v10
	v_add_f32_e32 v14, v89, v10
	v_cvt_pk_bf16_f32 v158, v84, v85
	v_cvt_pk_bf16_f32 v159, v86, v87
	ds_read_b64_tr_b16 v[10:11], v0 offset:25600
	ds_read_b64_tr_b16 v[12:13], v0 offset:26112
	v_add_f32_e32 v14, v90, v14
	v_add_f32_e32 v14, v91, v14
	v_add_f32_e32 v14, v92, v14
	v_add_f32_e32 v14, v93, v14
	v_cvt_pk_bf16_f32 v152, v88, v89
	v_cvt_pk_bf16_f32 v153, v90, v91
	v_mfma_f32_32x32x16_bf16 v[96:111], v[180:183], v[136:139], v[96:111]
	ds_read_b64_tr_b16 v[112:113], v0 offset:29696
	ds_read_b64_tr_b16 v[114:115], v0 offset:30208
	v_mfma_f32_32x32x16_bf16 v[48:63], v[176:179], v[136:139], v[48:63]
	v_add_f32_e32 v14, v94, v14
	v_add_f32_e32 v14, v95, v14
	v_add_f32_e32 v14, v64, v14
	v_add_f32_e32 v14, v65, v14
	v_cvt_pk_bf16_f32 v154, v92, v93
	v_cvt_pk_bf16_f32 v155, v94, v95
	ds_read_b64_tr_b16 v[116:117], v0 offset:26624
	ds_read_b64_tr_b16 v[118:119], v0 offset:27136
	v_add_f32_e32 v14, v66, v14
	v_add_f32_e32 v14, v67, v14
	v_add_f32_e32 v14, v68, v14
	v_add_f32_e32 v14, v69, v14
	v_cvt_pk_bf16_f32 v148, v64, v65
	v_cvt_pk_bf16_f32 v149, v66, v67
	v_mfma_f32_32x32x16_bf16 v[96:111], v[172:175], v[132:135], v[96:111]
	ds_read_b64_tr_b16 v[120:121], v0 offset:30720
	ds_read_b64_tr_b16 v[122:123], v0 offset:31232
	v_mfma_f32_32x32x16_bf16 v[48:63], v[168:171], v[132:135], v[48:63]
	v_add_f32_e32 v14, v70, v14
	v_add_f32_e32 v14, v71, v14
	v_add_f32_e32 v14, v72, v14
	v_add_f32_e32 v14, v73, v14
	v_cvt_pk_bf16_f32 v150, v68, v69
	v_cvt_pk_bf16_f32 v151, v70, v71
	ds_read_b64_tr_b16 v[124:125], v0 offset:27648
	ds_read_b64_tr_b16 v[126:127], v0 offset:28160
	v_add_f32_e32 v14, v74, v14
	v_add_f32_e32 v14, v75, v14
	v_add_f32_e32 v14, v76, v14
	v_add_f32_e32 v14, v77, v14
	v_cvt_pk_bf16_f32 v144, v72, v73
	v_cvt_pk_bf16_f32 v145, v74, v75
	v_mfma_f32_32x32x16_bf16 v[96:111], v[164:167], v[128:131], v[96:111]
	ds_read_b64_tr_b16 v[132:133], v0 offset:31744
	ds_read_b64_tr_b16 v[134:135], v0 offset:32256
	v_mfma_f32_32x32x16_bf16 v[48:63], v[160:163], v[128:131], v[48:63]
	v_add_f32_e32 v0, v78, v14
	v_add_f32_e32 v0, v79, v0
	v_add_f32_e32 v0, 0, v0
	v_cvt_pk_bf16_f32 v146, v76, v77
	v_cvt_pk_bf16_f32 v147, v78, v79
	v_lshl_add_u32 v14, s35, 8, v236
	v_add_u32_e32 v15, 0xffffff00, v14
	v_add_u32_e32 v68, 0xffffff80, v14
	ds_read_b128 v[64:67], v15
	ds_read_b128 v[68:71], v68
	v_add_u32_e32 v15, 0xffffff20, v14
	v_add_u32_e32 v76, 0xffffffa0, v14
	ds_read_b128 v[72:75], v15
	ds_read_b128 v[76:79], v76
	v_add_u32_e32 v15, 0xffffff40, v14
	v_subrev_u32_e32 v84, 64, v14
	ds_read_b128 v[80:83], v15
	ds_read_b128 v[84:87], v84
	v_add_u32_e32 v15, 0xffffff60, v14
	v_subrev_u32_e32 v14, 32, v14
	ds_read_b128 v[88:91], v15
	ds_read_b128 v[92:95], v14
	s_waitcnt lgkmcnt(7)
	v_pk_add_f32 v[14:15], v[98:99], v[66:67]
	v_or_b32_e32 v67, 0xe0, v221
	s_waitcnt lgkmcnt(6)
	v_pk_add_f32 v[48:49], v[48:49], v[68:69]
	v_or_b32_e32 v66, 0xc0, v221
	v_cmp_le_i32_e32 vcc, v67, v223
	v_pk_add_f32 v[64:65], v[96:97], v[64:65]
	v_pk_add_f32 v[50:51], v[50:51], v[70:71]
	v_cndmask_b32_e32 v48, v246, v48, vcc
	v_cmp_lt_i32_e32 vcc, v66, v223
	s_waitcnt lgkmcnt(5)
	v_pk_add_f32 v[72:73], v[100:101], v[72:73]
	s_waitcnt lgkmcnt(4)
	v_pk_add_f32 v[52:53], v[52:53], v[76:77]
	v_cndmask_b32_e32 v65, v246, v65, vcc
	v_cmp_le_i32_e32 vcc, v66, v223
	v_or_b32_e32 v66, 0xe1, v221
	v_pk_add_f32 v[74:75], v[102:103], v[74:75]
	v_cndmask_b32_e32 v64, v246, v64, vcc
	v_cmp_le_i32_e32 vcc, v66, v223
	v_or_b32_e32 v66, 0xc2, v221
	v_pk_add_f32 v[54:55], v[54:55], v[78:79]
	v_cndmask_b32_e32 v49, v246, v49, vcc
	v_cmp_le_i32_e32 vcc, v66, v223
	s_waitcnt lgkmcnt(3)
; __device__ __forceinline__ void cmask(f32x16&p0,f32x16&p1,int jb,int qrel,int hi){
;   const float NEG=-INFINITY; int kb=64*jb+4*hi;
;   #pragma unroll
;   for(int r=0;r<16;++r){int kv=kb+(r&3)+8*(r>>2); if(kv>qrel)p0[r]=NEG; if(kv+32>qrel)p1[r]=NEG;}
; }
	v_pk_add_f32 v[80:81], v[104:105], v[80:81]
	s_waitcnt lgkmcnt(2)
	v_pk_add_f32 v[56:57], v[56:57], v[84:85]
	v_cndmask_b32_e32 v66, v246, v14, vcc
	v_or_b32_e32 v14, 0xe2, v221
	v_cmp_le_i32_e32 vcc, v14, v223
	v_or_b32_e32 v14, 0xc3, v221
	v_pk_add_f32 v[82:83], v[106:107], v[82:83]
	v_cndmask_b32_e32 v50, v246, v50, vcc
	v_cmp_le_i32_e32 vcc, v14, v223
	v_or_b32_e32 v14, 0xe3, v221
	v_pk_add_f32 v[58:59], v[58:59], v[86:87]
	v_cndmask_b32_e32 v67, v246, v15, vcc
	v_cmp_le_i32_e32 vcc, v14, v223
	v_or_b32_e32 v14, 0xc8, v221
	s_waitcnt lgkmcnt(1)
	v_pk_add_f32 v[88:89], v[108:109], v[88:89]
	v_cndmask_b32_e32 v51, v246, v51, vcc
	v_cmp_le_i32_e32 vcc, v14, v223
	v_or_b32_e32 v14, 0xe8, v221
	s_waitcnt lgkmcnt(0)
	v_pk_add_f32 v[60:61], v[60:61], v[92:93]
	v_cndmask_b32_e32 v68, v246, v72, vcc
	v_cmp_le_i32_e32 vcc, v14, v223
	v_or_b32_e32 v14, 0xc9, v221
	v_pk_add_f32 v[90:91], v[110:111], v[90:91]
	v_cndmask_b32_e32 v52, v246, v52, vcc
	v_cmp_le_i32_e32 vcc, v14, v223
	v_or_b32_e32 v14, 0xe9, v221
	v_pk_add_f32 v[62:63], v[62:63], v[94:95]
	v_cndmask_b32_e32 v69, v246, v73, vcc
	v_cmp_le_i32_e32 vcc, v14, v223
	v_or_b32_e32 v14, 0xca, v221
	v_max3_f32 v15, v66, v67, v49
	v_cndmask_b32_e32 v53, v246, v53, vcc
	v_cmp_le_i32_e32 vcc, v14, v223
	v_or_b32_e32 v14, 0xea, v221
	v_add_f32_e32 v0, v230, v0
	v_cndmask_b32_e32 v70, v246, v74, vcc
	v_cmp_le_i32_e32 vcc, v14, v223
	v_or_b32_e32 v14, 0xcb, v221
	s_nop 0
	v_cndmask_b32_e32 v54, v246, v54, vcc
	v_cmp_le_i32_e32 vcc, v14, v223
	v_or_b32_e32 v14, 0xeb, v221
	s_nop 0
	v_cndmask_b32_e32 v71, v246, v75, vcc
	v_cmp_le_i32_e32 vcc, v14, v223
	v_or_b32_e32 v14, 0xd0, v221
	v_max3_f32 v15, v15, v70, v71
	v_cndmask_b32_e32 v55, v246, v55, vcc
	v_cmp_le_i32_e32 vcc, v14, v223
	v_or_b32_e32 v14, 0xf0, v221
	v_max3_f32 v15, v15, v54, v55
	v_cndmask_b32_e32 v72, v246, v80, vcc
	v_cmp_le_i32_e32 vcc, v14, v223
	v_or_b32_e32 v14, 0xd1, v221
	s_nop 0
	v_cndmask_b32_e32 v56, v246, v56, vcc
	v_cmp_le_i32_e32 vcc, v14, v223
	v_or_b32_e32 v14, 0xf1, v221
	s_nop 0
	v_cndmask_b32_e32 v73, v246, v81, vcc
	v_cmp_le_i32_e32 vcc, v14, v223
	v_or_b32_e32 v14, 0xd2, v221
	s_nop 0
	v_cndmask_b32_e32 v57, v246, v57, vcc
	v_cmp_le_i32_e32 vcc, v14, v223
	v_or_b32_e32 v14, 0xf2, v221
	s_nop 0
	v_cndmask_b32_e32 v74, v246, v82, vcc
	v_cmp_le_i32_e32 vcc, v14, v223
	v_or_b32_e32 v14, 0xd3, v221
	s_nop 0
	v_cndmask_b32_e32 v58, v246, v58, vcc
	v_cmp_le_i32_e32 vcc, v14, v223
	v_or_b32_e32 v14, 0xf3, v221
	s_nop 0
	v_cndmask_b32_e32 v75, v246, v83, vcc
	v_cmp_le_i32_e32 vcc, v14, v223
	v_or_b32_e32 v14, 0xd8, v221
	v_max3_f32 v15, v15, v74, v75
	v_cndmask_b32_e32 v59, v246, v59, vcc
	v_cmp_le_i32_e32 vcc, v14, v223
	v_or_b32_e32 v14, 0xf8, v221
	v_max3_f32 v15, v15, v58, v59
	v_cndmask_b32_e32 v76, v246, v88, vcc
	v_cmp_le_i32_e32 vcc, v14, v223
	v_or_b32_e32 v14, 0xd9, v221
	s_nop 0
	v_cndmask_b32_e32 v60, v246, v60, vcc
	v_cmp_le_i32_e32 vcc, v14, v223
	v_or_b32_e32 v14, 0xf9, v221
	s_nop 0
	v_cndmask_b32_e32 v77, v246, v89, vcc
	v_cmp_le_i32_e32 vcc, v14, v223
	v_or_b32_e32 v14, 0xda, v221
	s_nop 0
	v_cndmask_b32_e32 v61, v246, v61, vcc
	v_cmp_le_i32_e32 vcc, v14, v223
	v_or_b32_e32 v14, 0xfa, v221
	s_nop 0
	v_cndmask_b32_e32 v78, v246, v90, vcc
	v_cmp_le_i32_e32 vcc, v14, v223
	v_or_b32_e32 v14, 0xdb, v221
	s_nop 0
	v_cndmask_b32_e32 v62, v246, v62, vcc
	v_cmp_le_i32_e32 vcc, v14, v223
	v_or_b32_e32 v14, 0xfb, v221
	s_nop 0
	v_cndmask_b32_e32 v79, v246, v91, vcc
	v_cmp_le_i32_e32 vcc, v14, v223
	v_max_f32_e32 v14, v64, v65
	v_max3_f32 v14, v14, v48, v50
	v_max3_f32 v14, v14, v51, v68
	v_max3_f32 v14, v14, v69, v52
	v_max3_f32 v14, v14, v53, v72
	v_max3_f32 v14, v14, v73, v56
	v_cndmask_b32_e32 v63, v246, v63, vcc
	v_max3_f32 v14, v14, v57, v76
	v_max3_f32 v15, v15, v78, v79
	v_max3_f32 v14, v14, v77, v60
	v_max3_f32 v15, v15, v62, v63
	v_max3_f32 v14, v14, v61, v15
	v_mov_b32_e32 v15, v14
	s_nop 1
	v_permlane32_swap_b32_e32 v14, v15
	v_max_f32_e32 v14, v14, v15
	v_cmp_lt_f32_e32 vcc, s96, v14
	s_cmp_lg_u64 vcc, 0
	s_cselect_b64 s[4:5], -1, 0
	s_cbranch_vccnz .LBB0_412

.LBB0_280:
	s_waitcnt lgkmcnt(7)
	v_mfma_f32_32x32x16_bf16 v[144:159], v[220:223], v[184:187], v[80:95]
	v_add_f32_e32 v2, v112, v113
	v_add_f32_e32 v2, v114, v2
	v_add_f32_e32 v2, v115, v2
	s_lshl_b32 s72, s72, 1
	v_add_f32_e32 v2, v116, v2
	v_add_u32_e32 v0, s72, v245
	v_add_f32_e32 v2, v117, v2
	v_cvt_pk_bf16_f32 v188, v112, v113
	v_cvt_pk_bf16_f32 v189, v114, v115
	s_waitcnt lgkmcnt(6)
	v_mfma_f32_32x32x16_bf16 v[128:143], v[212:215], v[184:187], v[80:95]
	v_add_f32_e32 v2, v118, v2
	v_add_f32_e32 v2, v119, v2
	v_add_f32_e32 v2, v120, v2
	v_add_f32_e32 v2, v121, v2
	v_cvt_pk_bf16_f32 v190, v116, v117
	v_cvt_pk_bf16_f32 v191, v118, v119
	s_waitcnt lgkmcnt(5)
	v_mfma_f32_32x32x16_bf16 v[144:159], v[216:219], v[176:179], v[144:159]
	v_add_f32_e32 v2, v122, v2
	v_add_f32_e32 v2, v123, v2
	v_add_f32_e32 v2, v124, v2
	v_add_f32_e32 v2, v125, v2
	v_cvt_pk_bf16_f32 v180, v120, v121
	v_cvt_pk_bf16_f32 v181, v122, v123
	s_waitcnt lgkmcnt(4)
	v_mfma_f32_32x32x16_bf16 v[128:143], v[204:207], v[176:179], v[128:143]
	v_add_f32_e32 v2, v126, v2
	v_add_f32_e32 v2, v127, v2
	v_add_f32_e32 v2, v96, v2
	v_add_f32_e32 v2, v97, v2
	v_cvt_pk_bf16_f32 v182, v124, v125
	v_cvt_pk_bf16_f32 v183, v126, v127
	s_waitcnt lgkmcnt(3)
	v_mfma_f32_32x32x16_bf16 v[144:159], v[208:211], v[172:175], v[144:159]
	v_add_f32_e32 v2, v98, v2
	v_add_f32_e32 v2, v99, v2
	v_add_f32_e32 v2, v100, v2
	v_add_f32_e32 v2, v101, v2
	v_cvt_pk_bf16_f32 v168, v96, v97
	v_cvt_pk_bf16_f32 v169, v98, v99
	s_waitcnt lgkmcnt(2)
	v_mfma_f32_32x32x16_bf16 v[128:143], v[200:203], v[172:175], v[128:143]
	v_add_f32_e32 v2, v102, v2
	v_add_f32_e32 v2, v103, v2
	v_add_f32_e32 v2, v104, v2
	v_add_f32_e32 v6, v105, v2
	v_cvt_pk_bf16_f32 v170, v100, v101
	v_cvt_pk_bf16_f32 v171, v102, v103
	ds_read_b64_tr_b16 v[2:3], v0 offset:24576
	ds_read_b64_tr_b16 v[4:5], v0 offset:25088
	s_waitcnt lgkmcnt(3)
	v_mfma_f32_32x32x16_bf16 v[144:159], v[196:199], v[164:167], v[144:159]
	v_add_f32_e32 v6, v106, v6
	v_add_f32_e32 v6, v107, v6
	v_add_f32_e32 v6, v108, v6
	v_add_f32_e32 v10, v109, v6
	v_cvt_pk_bf16_f32 v160, v104, v105
	v_cvt_pk_bf16_f32 v161, v106, v107
	ds_read_b64_tr_b16 v[6:7], v0 offset:28672
	ds_read_b64_tr_b16 v[8:9], v0 offset:29184
	s_waitcnt lgkmcnt(4)
	v_mfma_f32_32x32x16_bf16 v[128:143], v[192:195], v[164:167], v[128:143]
	ds_read_b64_tr_b16 v[100:101], v0 offset:32768
	ds_read_b64_tr_b16 v[102:103], v0 offset:33280
	ds_read_b64_tr_b16 v[104:105], v0 offset:36864
	ds_read_b64_tr_b16 v[106:107], v0 offset:37376
	ds_read_b64_tr_b16 v[112:113], v0 offset:25600
	ds_read_b64_tr_b16 v[114:115], v0 offset:26112
	ds_read_b64_tr_b16 v[116:117], v0 offset:29696
	ds_read_b64_tr_b16 v[118:119], v0 offset:30208
	v_add_f32_e32 v10, v110, v10
	v_add_f32_e32 v10, v111, v10
	v_add_f32_e32 v12, 0, v10
	v_cvt_pk_bf16_f32 v162, v108, v109
	v_cvt_pk_bf16_f32 v163, v110, v111
	v_lshl_add_u64 v[14:15], v[234:235], 0, s[6:7]
	v_lshl_add_u64 v[10:11], v[14:15], 0, s[56:57]
	s_add_i32 s72, s78, s64
	v_lshl_add_u64 v[208:209], v[236:237], 0, s[6:7]
	s_mov_b32 s73, m0
	s_mov_b32 m0, s72
	s_nop 0
	global_load_lds_dwordx4 v[10:11], off
	s_mov_b32 m0, s73
	v_lshl_add_u64 v[10:11], v[208:209], 0, s[48:49]
	s_lshl_b32 s72, s76, 1
	v_lshl_add_u64 v[210:211], v[238:239], 0, s[6:7]
	s_add_i32 s72, s72, s63
	s_mov_b32 s73, m0
	s_mov_b32 m0, s72
	s_nop 0
	global_load_lds_dwordx4 v[10:11], off
	s_mov_b32 m0, s73
	v_lshl_add_u64 v[10:11], v[210:211], 0, s[48:49]
	s_addk_i32 s72, 0x2000
	s_mov_b32 s73, m0
	s_mov_b32 m0, s72
	s_nop 0
	global_load_lds_dwordx4 v[10:11], off
	s_mov_b32 m0, s73
	v_max_f32_e32 v10, v144, v145
	v_max3_f32 v11, v146, v147, v129
	v_max3_f32 v10, v10, v128, v130
	v_max3_f32 v10, v10, v131, v148
	v_max3_f32 v11, v11, v150, v151
	v_max3_f32 v10, v10, v149, v132
	v_max3_f32 v11, v11, v134, v135
	v_max3_f32 v10, v10, v133, v152
	v_max3_f32 v11, v11, v154, v155
	v_max3_f32 v10, v10, v153, v136
	v_max3_f32 v11, v11, v138, v139
	v_max3_f32 v10, v10, v137, v156
	v_max3_f32 v11, v11, v158, v159
	v_max3_f32 v10, v10, v157, v140
	v_max3_f32 v11, v11, v142, v143
	v_max3_f32 v10, v10, v141, v11
	v_mov_b32_e32 v11, v10
	s_nop 1
	v_permlane32_swap_b32_e32 v10, v11
	v_max_f32_e32 v10, v10, v11
	v_cmp_lt_f32_e32 vcc, s96, v10
	s_cmp_lg_u64 vcc, 0
	v_add_f32_e32 v212, v231, v12
	s_cselect_b64 s[72:73], -1, 0
	s_cbranch_vccnz .LBB0_288

.LBB0_283:
	s_add_i32 s72, s76, 0x2000
	s_cmpk_lg_i32 s76, 0x4000
	s_cselect_b32 s87, s72, 0
	v_mfma_f32_32x32x16_bf16 v[112:127], v[96:99], v[184:187], v[80:95]
	v_add_f32_e32 v100, v144, v145
	v_add_f32_e32 v100, v146, v100
	v_add_f32_e32 v100, v147, v100
	s_lshl_b32 s72, s78, 1
	v_add_f32_e32 v100, v148, v100
	v_add_u32_e32 v233, s72, v245
	v_add_f32_e32 v96, v149, v100
	v_cvt_pk_bf16_f32 v188, v144, v145
	v_cvt_pk_bf16_f32 v189, v146, v147
	s_nop 0
	v_add_f32_e32 v96, v150, v96
	v_add_f32_e32 v96, v151, v96
	v_add_f32_e32 v96, v152, v96
	v_add_f32_e32 v144, v153, v96
	v_mfma_f32_32x32x16_bf16 v[96:111], v[10:13], v[184:187], v[80:95]
	v_cvt_pk_bf16_f32 v190, v148, v149
	v_cvt_pk_bf16_f32 v191, v150, v151
	v_mfma_f32_32x32x16_bf16 v[112:127], v[204:207], v[176:179], v[112:127]
	v_add_f32_e32 v10, v154, v144
	v_add_f32_e32 v10, v155, v10
	v_add_f32_e32 v10, v156, v10
	v_add_f32_e32 v10, v157, v10
	v_cvt_pk_bf16_f32 v180, v152, v153
	v_cvt_pk_bf16_f32 v181, v154, v155
	v_mfma_f32_32x32x16_bf16 v[96:111], v[192:195], v[176:179], v[96:111]
	v_add_f32_e32 v10, v158, v10
	v_add_f32_e32 v10, v159, v10
	v_add_f32_e32 v10, v128, v10
	v_add_f32_e32 v10, v129, v10
	v_cvt_pk_bf16_f32 v182, v156, v157
	v_cvt_pk_bf16_f32 v183, v158, v159
	v_mfma_f32_32x32x16_bf16 v[112:127], v[200:203], v[172:175], v[112:127]
	v_add_f32_e32 v10, v130, v10
	v_add_f32_e32 v10, v131, v10
	v_add_f32_e32 v10, v132, v10
	v_add_f32_e32 v10, v133, v10
	v_cvt_pk_bf16_f32 v168, v128, v129
	v_cvt_pk_bf16_f32 v169, v130, v131
	v_mfma_f32_32x32x16_bf16 v[96:111], v[6:9], v[172:175], v[96:111]
	v_add_f32_e32 v6, v134, v10
	v_add_f32_e32 v6, v135, v6
	v_add_f32_e32 v6, v136, v6
	v_add_f32_e32 v10, v137, v6
	v_cvt_pk_bf16_f32 v170, v132, v133
	v_cvt_pk_bf16_f32 v171, v134, v135
	ds_read_b64_tr_b16 v[6:7], v233 offset:24576
	ds_read_b64_tr_b16 v[8:9], v233 offset:25088
	v_mfma_f32_32x32x16_bf16 v[112:127], v[196:199], v[164:167], v[112:127]
	v_add_f32_e32 v10, v138, v10
	v_add_f32_e32 v10, v139, v10
	v_add_f32_e32 v10, v140, v10
	v_add_f32_e32 v128, v141, v10
	v_cvt_pk_bf16_f32 v160, v136, v137
	v_cvt_pk_bf16_f32 v161, v138, v139
	ds_read_b64_tr_b16 v[10:11], v233 offset:28672
	ds_read_b64_tr_b16 v[12:13], v233 offset:29184
	v_mfma_f32_32x32x16_bf16 v[96:111], v[2:5], v[164:167], v[96:111]
	ds_read_b64_tr_b16 v[144:145], v233 offset:32768
	ds_read_b64_tr_b16 v[146:147], v233 offset:33280
	ds_read_b64_tr_b16 v[148:149], v233 offset:36864
	ds_read_b64_tr_b16 v[150:151], v233 offset:37376
	ds_read_b64_tr_b16 v[152:153], v233 offset:25600
	ds_read_b64_tr_b16 v[154:155], v233 offset:26112
	ds_read_b64_tr_b16 v[156:157], v233 offset:29696
	ds_read_b64_tr_b16 v[158:159], v233 offset:30208
	v_add_f32_e32 v2, v142, v128
	v_add_f32_e32 v2, v143, v2
	v_add_f32_e32 v4, 0, v2
	v_cvt_pk_bf16_f32 v162, v140, v141
	v_cvt_pk_bf16_f32 v163, v142, v143
	v_lshl_add_u64 v[2:3], v[14:15], 0, s[52:53]
	s_add_i32 s72, s76, s64
	s_mov_b32 s73, m0
	s_mov_b32 m0, s72
	s_nop 0
	global_load_lds_dwordx4 v[2:3], off
	s_mov_b32 m0, s73
	v_lshl_add_u64 v[2:3], v[208:209], 0, s[50:51]
	s_lshl_b32 s72, s87, 1
	s_add_i32 s72, s72, s63
	s_mov_b32 s73, m0
	s_mov_b32 m0, s72
	s_nop 0
	global_load_lds_dwordx4 v[2:3], off
	s_mov_b32 m0, s73
	v_lshl_add_u64 v[2:3], v[210:211], 0, s[50:51]
	s_addk_i32 s72, 0x2000
	s_mov_b32 s73, m0
	s_mov_b32 m0, s72
	s_nop 0
	global_load_lds_dwordx4 v[2:3], off
	s_mov_b32 m0, s73
	v_max_f32_e32 v2, v112, v113
	v_max3_f32 v3, v114, v115, v97
	v_max3_f32 v2, v2, v96, v98
	v_max3_f32 v2, v2, v99, v116
	v_max3_f32 v3, v3, v118, v119
	v_max3_f32 v2, v2, v117, v100
	v_max3_f32 v3, v3, v102, v103
	v_max3_f32 v2, v2, v101, v120
	v_max3_f32 v3, v3, v122, v123
	v_max3_f32 v2, v2, v121, v104
	v_max3_f32 v3, v3, v106, v107
	v_max3_f32 v2, v2, v105, v124
	v_max3_f32 v3, v3, v126, v127
	v_max3_f32 v2, v2, v125, v108
	v_max3_f32 v3, v3, v110, v111
	v_max3_f32 v2, v2, v109, v3
	v_mov_b32_e32 v3, v2
	s_nop 1
	v_permlane32_swap_b32_e32 v2, v3
	v_max_f32_e32 v2, v2, v3
	v_cmp_lt_f32_e32 vcc, s96, v2
	s_cmp_lg_u64 vcc, 0
	v_add_f32_e32 v231, v212, v4
	s_cselect_b64 s[72:73], -1, 0
	s_cbranch_vccnz .LBB0_291
